# CONV5: conv row-request block gets a fast path for latent items (precomputed per-lane row*pitch offsets, no predicate VALU); on top of CONV3
# speedup vs baseline: 1.0132x; 1.0132x over previous
; #define LAS __attribute__((address_space(3)))
; __device__ __forceinline__ float bf2f(unsigned short b) { return __uint_as_float(((unsigned)b) << 16); }
; __device__ __forceinline__ float log1p_small(float e) { return e < 0.03f ? e * (1.f - e * (0.5f - e * (0.33333334f - 0.25f * e))) : __logf(1.f + e); }
; __device__ __forceinline__ void conv_fetch(const bf16_t* raw, int item, int tid, u32x4 (&rg)[3]) {
;     constexpr int NFB = 80;
;     const int ch = item / NFB, fb = item % NFB;
;     const bool is_ctx = ch < (CGR / 128);
;     const long row0 = (long)ch * 128;
; #pragma unroll
;     for (int i = 0; i < 3; ++i) {
;         const int idx = tid + 512 * i;
;         rg[i] = (u32x4){0u, 0u, 0u, 0u};
;         if (idx < 134 * 8) { const int ir = idx >> 3, c8 = idx & 7; int tok; bool ok;
;             if (is_ctx) { tok = ir - 2; const int gt = (ch & 1) * 128 + tok; ok = (ir < 131) && gt >= 0 && gt < 256; }
;             else { const int sg = ir >= 67 ? 1 : 0, q = ir - 67 * sg; tok = 64 * sg + q - 2; ok = q >= 2 && q < 66; }
;             if (ok) rg[i] = *(const u32x4*)(raw + (size_t)(row0 + tok) * NA + fb * 64 + c8 * 8); }
; __device__ __forceinline__ void phase_conv(const Params& p, LAS unsigned char* lds, int wg, int G, int tid) {
;     const bf16_t* raw = (const bf16_t*)(p.ws + OFF_RAW);
;     bf16_t* xT = (bf16_t*)(p.ws + OFF_XT); bf16_t* bm = (bf16_t*)(p.ws + OFF_BM); bf16_t* bT = (bf16_t*)(p.ws + OFF_BT);
;     bf16_t* cm = (bf16_t*)(p.ws + OFF_CM); bf16_t* uu = (bf16_t*)(p.ws + OFF_U); float* dt = (float*)(p.ws + OFF_DT);
;     constexpr int NCH = RG / 128, NFB = 80, NIT = NCH * NFB;
;     const int f = tid & 63, tg = tid >> 6;
;     for (int ch = wg; ch < NCH; ch += G) {
;         const float bias = p.ssd_dt_bias[f];
;         unsigned short rv[16];
; #pragma unroll
;         for (int k = 0; k < 16; ++k) rv[k] = raw[((size_t)ch * 128 + tg * 16 + k) * NA + 5120 + f];
; #pragma unroll
;         for (int k = 0; k < 16; ++k) { const size_t row = (size_t)ch * 128 + tg * 16 + k; const float v = bf2f(rv[k]) + bias;
;             dt[row * 64 + f] = v > 20.f ? v : log1p_small(__expf(v)); }
;     }
;     u32x4 rg[3];
;     int item = wg, buf = 0;
;     if (item < NIT) conv_fetch(raw, item, tid, rg);
.LBB0_625:
	s_andn2_b64 vcc, exec, s[4:5]
	s_cbranch_vccnz .LBB0_674
	v_lshlrev_b32_e32 v12, 3, v240
	v_and_b32_e32 v50, 56, v12
	v_lshlrev_b32_e32 v192, 1, v50
	v_lshl_add_u64 v[20:21], s[0:1], 0, v[192:193]
	s_movk_i32 s0, 0x430
	v_cmp_gt_i32_e64 s[2:3], s0, v240
	v_ashrrev_i32_e32 v13, 3, v240
	s_movk_i32 s0, 0x42
	v_cmp_lt_i32_e32 vcc, s0, v13
	v_mov_b32_e32 v17, 0xffffffbd
	v_add_u32_e32 v51, -2, v13
	v_cndmask_b32_e32 v14, 0, v17, vcc
	s_movk_i32 s1, 0x83
	v_cndmask_b32_e64 v15, 0, 64, vcc
	v_add_u32_e32 v14, v14, v51
	v_cmp_gt_i32_e64 s[6:7], s1, v13
	v_add_u32_e32 v13, 0x200, v240
	v_add_u32_e32 v52, v14, v15
	v_cmp_gt_u32_e64 s[4:5], 64, v14
	v_ashrrev_i32_e32 v14, 3, v13
	v_cmp_lt_i32_e32 vcc, s0, v14
	v_add_u32_e32 v53, -2, v14
	v_cmp_gt_i32_e64 s[12:13], s1, v14
	v_cndmask_b32_e32 v15, 0, v17, vcc
	v_cndmask_b32_e64 v16, 0, 64, vcc
	v_add_u32_e32 v15, v15, v53
	v_add_u32_e32 v14, 0x400, v240
	v_add_u32_e32 v54, v15, v16
	v_cmp_gt_u32_e64 s[10:11], 64, v15
	v_ashrrev_i32_e32 v15, 3, v14
	v_cmp_lt_i32_e32 vcc, s0, v15
	v_add_u32_e32 v55, -2, v15
	v_cmp_gt_i32_e64 s[18:19], s1, v15
	v_cndmask_b32_e32 v16, 0, v17, vcc
	v_cndmask_b32_e64 v17, 0, 64, vcc
	v_add_u32_e32 v16, v16, v55
	v_add_u32_e32 v56, v16, v17
	v_cmp_gt_u32_e64 s[16:17], 64, v16
	v_ashrrev_i32_e32 v16, 2, v240
	v_lshrrev_b32_e32 v15, 8, v240
	v_and_b32_e32 v22, -8, v16
	v_and_b32_e32 v16, 56, v16
	s_movk_i32 s0, 0x43
	v_readlane_b32 s20, v255, 31
	v_mad_u32_u24 v59, v15, s0, v16
	v_readlane_b32 s21, v255, 32
	s_add_u32 s0, s20, 0x1000
	s_addc_u32 s1, s21, 0
	s_add_u32 s24, s20, 0x2000
	s_addc_u32 s25, s21, 0
	s_mov_b32 s93, s88
	s_mov_b32 s88, s26
	s_mov_b64 s[96:97], s[38:39]
	s_add_u32 s26, s20, 0x3000
	v_readlane_b32 s36, v255, 19
	s_addc_u32 s27, s21, 0
	v_readlane_b32 s38, v255, 21
	v_readlane_b32 s39, v255, 22
	s_add_u32 s28, s38, 0x4000
	s_addc_u32 s29, s39, 0
	s_add_u32 s30, s38, 0x8000
	v_and_b32_e32 v60, 0xffffffc0, v12
	v_lshlrev_b32_e32 v12, 3, v13
	s_addc_u32 s31, s39, 0
	s_movk_i32 s8, 0x230
	v_and_b32_e32 v57, 31, v245
	v_ashrrev_i32_e32 v23, 31, v22
	v_and_b32_e32 v61, 0xffffffc0, v12
	v_lshlrev_b32_e32 v12, 3, v14
	v_readlane_b32 s37, v255, 20
	v_readlane_b32 s41, v255, 24
	s_add_u32 s36, s38, 0xc000
	s_mov_b64 s[72:73], s[84:85]
	s_mov_b64 s[68:69], s[86:87]
	s_mov_b32 s54, s76
	s_mov_b64 s[76:77], s[60:61]
	s_mov_b64 s[60:61], s[44:45]
	s_mov_b32 s33, 0
	v_cmp_gt_i32_e64 s[8:9], s8, v240
	v_cmp_gt_i32_e64 s[14:15], 48, v240
	v_lshlrev_b32_e32 v58, 1, v57
	v_and_b32_e32 v62, 0xffffffc0, v12
	s_addc_u32 s37, s39, 0
	v_lshlrev_b64 v[24:25], 11, v[22:23]
	s_lshl_b32 s38, s92, 6
	s_lshl_b32 s39, s34, 6
	s_mov_b32 s41, s92
	v_readlane_b32 s22, v255, 33
	v_readlane_b32 s23, v255, 34
	v_readlane_b32 s40, v255, 23
	v_readlane_b32 s42, v255, 25
	v_readlane_b32 s43, v255, 26
	v_mad_i64_i32 v[80:81], s[20:21], v52, s78, 0
	v_mad_i64_i32 v[82:83], s[20:21], v54, s78, 0
	v_mad_i64_i32 v[84:85], s[20:21], v56, s78, 0
	s_add_i32 s40, s41, s34
	s_mul_hi_i32 s20, s40, 0x66666667
	s_lshr_b32 s21, s20, 31
	s_ashr_i32 s20, s20, 5
	s_add_i32 s20, s20, s21
	s_cmpk_lt_i32 s40, 0xa00
	s_cselect_b64 vcc, -1, 0
	s_ashr_i32 s21, s20, 31
	s_lshl_b64 s[22:23], s[20:21], 7
	s_lshl_b32 s21, s20, 7
	s_and_b32 s45, s21, 0x80
	s_mulk_i32 s20, 0xec00
	s_add_i32 s21, s39, s38
	s_add_i32 s20, s21, s20
	s_ashr_i32 s21, s20, 31
	v_lshl_add_u64 v[66:67], s[20:21], 1, v[20:21]
	s_cbranch_vccnz .Lconv_p_ctx
	s_mul_hi_u32 s49, s22, s78
	s_mul_i32 s48, s22, s78
	v_mov_b32_e32 v68, 0
	v_mov_b32_e32 v69, 0
	v_mov_b32_e32 v70, 0
	v_mov_b32_e32 v71, 0
	v_mov_b32_e32 v72, 0
	v_mov_b32_e32 v73, 0
	v_mov_b32_e32 v74, 0
	v_mov_b32_e32 v75, 0
	v_mov_b32_e32 v76, 0
	v_mov_b32_e32 v77, 0
	v_mov_b32_e32 v78, 0
	v_mov_b32_e32 v79, 0
	v_lshl_add_u64 v[66:67], v[66:67], 0, s[48:49]
	s_and_b64 s[20:21], s[2:3], s[4:5]
	s_and_saveexec_b64 s[50:51], s[20:21]
	v_lshl_add_u64 v[70:71], v[80:81], 0, v[66:67]
	global_load_dwordx4 v[68:71], v[70:71], off
	s_or_b64 exec, exec, s[50:51]
	s_and_b64 s[20:21], s[8:9], s[10:11]
	s_and_saveexec_b64 s[50:51], s[20:21]
	v_lshl_add_u64 v[74:75], v[82:83], 0, v[66:67]
	global_load_dwordx4 v[72:75], v[74:75], off
	s_or_b64 exec, exec, s[50:51]
	s_and_b64 s[20:21], s[14:15], s[16:17]
	s_and_saveexec_b64 s[50:51], s[20:21]
	v_lshl_add_u64 v[78:79], v[84:85], 0, v[66:67]
	global_load_dwordx4 v[76:79], v[78:79], off
	s_or_b64 exec, exec, s[50:51]
	s_branch .Lconv_p_done
.Lconv_p_ctx:
	v_mov_b32_e32 v72, 0
	v_mov_b32_e32 v68, 0
	v_mov_b32_e32 v69, 0
	v_mov_b32_e32 v70, 0
	v_mov_b32_e32 v71, 0
	s_and_saveexec_b64 s[48:49], s[2:3]
	s_cbranch_execz .Lconv_p_637
	v_add_u32_e32 v68, s45, v51
	s_movk_i32 s20, 0x100
	v_cmp_gt_u32_e64 s[20:21], s20, v68
	s_and_b64 s[20:21], s[6:7], s[20:21]
	v_cndmask_b32_e64 v69, 0, 1, s[4:5]
	v_cndmask_b32_e64 v68, 0, 1, s[20:21]
	v_cndmask_b32_e32 v68, v69, v68, vcc
	v_and_b32_e32 v68, 1, v68
	v_cmp_eq_u32_e64 s[20:21], 1, v68
	v_mov_b32_e32 v71, 0
	v_mov_b32_e32 v70, 0
	v_mov_b32_e32 v69, 0
	v_mov_b32_e32 v68, 0
	s_and_saveexec_b64 s[50:51], s[20:21]
	s_cbranch_execz .Lconv_p_636
	v_cndmask_b32_e32 v68, v52, v51, vcc
	v_ashrrev_i32_e32 v69, 31, v68
	v_lshl_add_u64 v[68:69], s[22:23], 0, v[68:69]
	v_mad_u64_u32 v[70:71], s[20:21], v68, s78, v[66:67]
	v_mad_i32_i24 v71, v69, s78, v71
	global_load_dwordx4 v[68:71], v[70:71], off

; __device__ __forceinline__ void phase_conv(const Params& p, LAS unsigned char* lds, int wg, int G, int tid) {
;     ...
;     int item = wg, buf = 0;
;     if (item < NIT) conv_fetch(raw, item, tid, rg);
;     for (; item < NIT; item += G) {
;     ...
;         buf ^= 1;
;     }
.Lconv_p_645:
	s_or_b64 exec, exec, s[48:49]
.Lconv_p_done:
	s_waitcnt vmcnt(0)
	s_branch .LBB0_628
.LBB0_627:
	s_xor_b32 s33, s33, 1
	s_add_i32 s38, s38, s39
	s_andn2_b64 vcc, exec, s[42:43]
	s_mov_b32 s41, s40
	s_cbranch_vccz .LBB0_673

; #define LAS __attribute__((address_space(3)))
; __device__ __forceinline__ void conv_fetch(const bf16_t* raw, int item, int tid, u32x4 (&rg)[3]) {
;     ...
;     for (int i = 0; i < 3; ++i) {
;         const int idx = tid + 512 * i;
;         rg[i] = (u32x4){0u, 0u, 0u, 0u};
;         if (idx < 134 * 8) { const int ir = idx >> 3, c8 = idx & 7; int tok; bool ok;
;             if (is_ctx) { tok = ir - 2; const int gt = (ch & 1) * 128 + tok; ok = (ir < 131) && gt >= 0 && gt < 256; }
;             else { const int sg = ir >= 67 ? 1 : 0, q = ir - 67 * sg; tok = 64 * sg + q - 2; ok = q >= 2 && q < 66; }
;             if (ok) rg[i] = *(const u32x4*)(raw + (size_t)(row0 + tok) * NA + fb * 64 + c8 * 8); }
; __device__ __forceinline__ void phase_conv(const Params& p, LAS unsigned char* lds, int wg, int G, int tid) {
;     ...
;         if (item + G < NIT) conv_fetch(raw, item + G, tid, rg);
;         const int ch = item / NFB, fb = item % NFB;
;         const size_t row0 = (size_t)ch * 128;
;         const int fp = tid & 31, tq = tid >> 5;
;         const int feat = fb * 64 + 2 * fp;
;         f32x2 w0, w1, w2, w3, bias;
;         if (feat < 4096) { w0 = *(const f32x2*)(p.ssd_conv_w + feat); w1 = *(const f32x2*)(p.ssd_conv_w + 4096 + feat); w2 = *(const f32x2*)(p.ssd_conv_w + 8192 + feat); w3 = *(const f32x2*)(p.ssd_conv_w + 12288 + feat); bias = *(const f32x2*)(p.ssd_conv_b + feat); }
;         else { const int lf = feat - 4096; w0 = *(const f32x2*)(p.lru_conv_w + lf); w1 = *(const f32x2*)(p.lru_conv_w + 1024 + lf); w2 = *(const f32x2*)(p.lru_conv_w + 2048 + lf); w3 = *(const f32x2*)(p.lru_conv_w + 3072 + lf); bias = *(const f32x2*)(p.lru_conv_b + lf); }
;         const bool is_ctx = ch < (CGR / 128);
;         const bool act = fb < 64;
;         f32x2 o[8];
;         const int ib0 = is_ctx ? tq * 8 : (tq >> 3) * 67 + (tq & 7) * 8;
;         const LAS f32x2* tp = (const LAS f32x2*)tile + fp;
;         f32x2 v0 = tp[(ib0 + 0) * 32], v1 = tp[(ib0 + 1) * 32], v2 = tp[(ib0 + 2) * 32];
; #pragma unroll
;         for (int k = 0; k < 8; ++k) {
;             const f32x2 v3 = tp[(ib0 + k + 3) * 32];
;             f32x2 a = bias + w0 * v0 + w1 * v1 + w2 * v2 + w3 * v3;
.LBB0_650:
	s_or_b64 exec, exec, s[20:21]
	global_load_dwordx2 v[30:31], v[12:13], off
	global_load_dwordx2 v[32:33], v[28:29], off
	global_load_dwordx2 v[38:39], v[14:15], off
	global_load_dwordx2 v[36:37], v[16:17], off
	global_load_dwordx2 v[34:35], v[18:19], off
	s_mul_i32 s20, s48, 0xffffffb0
	s_add_i32 s45, s41, s20
	s_cmpk_lt_i32 s41, 0xa00
	s_cselect_b64 s[20:21], -1, 0
	v_cndmask_b32_e64 v12, v59, v22, s[20:21]
	v_lshl_add_u32 v13, v57, 3, s44
	v_lshlrev_b32_e32 v12, 8, v12
	v_add_u32_e32 v27, v13, v12
	ds_read2_b64 v[16:19], v27 offset1:32
	ds_read2_b64 v[12:15], v27 offset0:64 offset1:96
	s_cmp_lt_i32 s45, 64
	s_cselect_b64 s[50:51], -1, 0
	s_cmp_gt_i32 s45, 63
	s_waitcnt vmcnt(3) lgkmcnt(1)
	v_pk_fma_f32 v[16:17], v[30:31], v[16:17], v[32:33]
	s_waitcnt vmcnt(2)
	v_pk_fma_f32 v[16:17], v[38:39], v[18:19], v[16:17]
	s_waitcnt vmcnt(1) lgkmcnt(0)
	v_pk_fma_f32 v[16:17], v[36:37], v[12:13], v[16:17]
	s_waitcnt vmcnt(0)
	v_pk_fma_f32 v[16:17], v[34:35], v[14:15], v[16:17]
	v_mov_b32_e32 v0, v68
	v_mov_b32_e32 v1, v69
	v_mov_b32_e32 v2, v70
	v_mov_b32_e32 v3, v71
	v_mov_b32_e32 v4, v72
	v_mov_b32_e32 v5, v73
	v_mov_b32_e32 v6, v74
	v_mov_b32_e32 v7, v75
	v_mov_b32_e32 v8, v76
	v_mov_b32_e32 v9, v77
	v_mov_b32_e32 v10, v78
	v_mov_b32_e32 v11, v79
	s_mov_b32 s101, s45
	v_writelane_b32 v255, s48, 63
	v_writelane_b32 v255, s50, 59
	v_writelane_b32 v255, s51, 60
	s_add_i32 s100, s40, s34
	s_cmpk_gt_i32 s100, 0x59ff
	s_cbranch_scc1 .Lconv_nopf
	s_mul_hi_i32 s20, s100, 0x66666667
	s_lshr_b32 s21, s20, 31
	s_ashr_i32 s20, s20, 5
	s_add_i32 s20, s20, s21
	s_cmpk_lt_i32 s100, 0xa00
	s_cselect_b64 vcc, -1, 0
	s_ashr_i32 s21, s20, 31
	s_lshl_b64 s[22:23], s[20:21], 7
	s_lshl_b32 s21, s20, 7
	s_and_b32 s45, s21, 0x80
	s_mulk_i32 s20, 0xec00
	s_add_i32 s21, s39, s38
	s_add_i32 s21, s21, s39
	s_add_i32 s20, s21, s20
	s_ashr_i32 s21, s20, 31
	v_lshl_add_u64 v[66:67], s[20:21], 1, v[20:21]
	s_cbranch_vccnz .Lconv_l_ctx
	s_mul_hi_u32 s49, s22, s78
	s_mul_i32 s48, s22, s78
	v_mov_b32_e32 v68, 0
	v_mov_b32_e32 v69, 0
	v_mov_b32_e32 v70, 0
	v_mov_b32_e32 v71, 0
	v_mov_b32_e32 v72, 0
	v_mov_b32_e32 v73, 0
	v_mov_b32_e32 v74, 0
	v_mov_b32_e32 v75, 0
	v_mov_b32_e32 v76, 0
	v_mov_b32_e32 v77, 0
	v_mov_b32_e32 v78, 0
	v_mov_b32_e32 v79, 0
	v_lshl_add_u64 v[66:67], v[66:67], 0, s[48:49]
	s_and_b64 s[20:21], s[2:3], s[4:5]
	s_and_saveexec_b64 s[50:51], s[20:21]
	v_lshl_add_u64 v[70:71], v[80:81], 0, v[66:67]
	global_load_dwordx4 v[68:71], v[70:71], off
	s_or_b64 exec, exec, s[50:51]
	s_and_b64 s[20:21], s[8:9], s[10:11]
	s_and_saveexec_b64 s[50:51], s[20:21]
	v_lshl_add_u64 v[74:75], v[82:83], 0, v[66:67]
	global_load_dwordx4 v[72:75], v[74:75], off
	s_or_b64 exec, exec, s[50:51]
	s_and_b64 s[20:21], s[14:15], s[16:17]
	s_and_saveexec_b64 s[50:51], s[20:21]
	v_lshl_add_u64 v[78:79], v[84:85], 0, v[66:67]
	global_load_dwordx4 v[76:79], v[78:79], off
	s_or_b64 exec, exec, s[50:51]
	s_branch .Lconv_l_done

; #define LAS __attribute__((address_space(3)))
; __device__ __forceinline__ void phase_conv(const Params& p, LAS unsigned char* lds, int wg, int G, int tid) {
;     ...
;         const int ib0 = is_ctx ? tq * 8 : (tq >> 3) * 67 + (tq & 7) * 8;
;         const LAS f32x2* tp = (const LAS f32x2*)tile + fp;
;         f32x2 v0 = tp[(ib0 + 0) * 32], v1 = tp[(ib0 + 1) * 32], v2 = tp[(ib0 + 2) * 32];
; #pragma unroll
;         for (int k = 0; k < 8; ++k) {
;             const f32x2 v3 = tp[(ib0 + k + 3) * 32];
;             f32x2 a = bias + w0 * v0 + w1 * v1 + w2 * v2 + w3 * v3;
;             if (act) { f32x2 d; d.x = 1.f + __expf(-a.x); d.y = 1.f + __expf(-a.y); f32x2 rc; rc.x = __builtin_amdgcn_rcpf(d.x); rc.y = __builtin_amdgcn_rcpf(d.y); a = a * rc; }
;             o[k] = a;
;             v0 = v1; v1 = v2; v2 = v3;
;         }
.Lconv_l_done:
.Lconv_nopf:
	v_readlane_b32 s50, v255, 59
	v_readlane_b32 s51, v255, 60
	v_readlane_b32 s48, v255, 63
	s_cmpk_lt_i32 s41, 0xa00
	s_cselect_b64 s[20:21], -1, 0
	s_mov_b32 s45, s101
	s_nop 3
	s_cmp_gt_i32 s45, 63
	s_cbranch_scc1 .LBB0_652
	v_mul_f32_e32 v28, 0xbfb8aa3b, v16
	v_mul_f32_e32 v29, 0xbfb8aa3b, v17
	v_exp_f32_e32 v28, v28
	v_exp_f32_e32 v29, v29
	v_add_f32_e32 v28, 1.0, v28
	v_add_f32_e32 v29, 1.0, v29
	v_rcp_f32_e32 v28, v28
	v_rcp_f32_e32 v29, v29
	s_nop 0
	v_pk_mul_f32 v[16:17], v[16:17], v[28:29]
